# combo5 + IDX chunk loop: counted wait instead of per-chunk vmcnt(0) drain + PR1 row loads issued before the previous-row wait
# speedup vs baseline: 1.0011x; 1.0011x over previous
.LBB0_572:
	s_lshl_b32 s42, s33, 5
	s_add_u32 s2, s34, s42
	s_addc_u32 s14, s35, 0
	v_mov_b32_e32 v3, s14
	v_or_b32_e32 v2, s2, v114
	v_lshlrev_b64 v[2:3], 10, v[2:3]
	v_lshl_add_u64 v[2:3], v[116:117], 0, v[2:3]
	global_load_dwordx4 v[66:69], v[2:3], off
	global_load_dwordx4 v[70:73], v[2:3], off offset:32
	global_load_dwordx4 v[74:77], v[2:3], off offset:64
	global_load_dwordx4 v[78:81], v[2:3], off offset:96
	v_mov_b32_e32 v3, s14
	v_or_b32_e32 v2, s2, v118
	v_lshlrev_b64 v[2:3], 5, v[2:3]
	v_lshl_add_u64 v[4:5], s[18:19], 0, v[2:3]
	global_load_dwordx4 v[82:85], v[4:5], off offset:16
	global_load_dwordx4 v[86:89], v[4:5], off
	v_or_b32_e32 v2, 32, v2
	v_lshl_add_u64 v[2:3], s[18:19], 0, v[2:3]
	global_load_dwordx4 v[98:101], v[120:121], off
	global_load_dwordx4 v[102:105], v[122:123], off
	global_load_dwordx4 v[106:109], v[124:125], off
	global_load_dwordx4 v[110:113], v[126:127], off
	global_load_dwordx4 v[90:93], v[2:3], off offset:16
	global_load_dwordx4 v[94:97], v[2:3], off
	s_waitcnt lgkmcnt(0)
	s_barrier
	s_cmp_gt_u32 s33, 7
	s_waitcnt vmcnt(5)
	ds_write_b128 v160, v[98:101]
	s_waitcnt vmcnt(4)
	ds_write_b128 v160, v[102:105] offset:8192
	s_waitcnt vmcnt(3)
	ds_write_b128 v160, v[106:109] offset:16384
	s_waitcnt vmcnt(2)
	ds_write_b128 v160, v[110:113] offset:24576
	s_waitcnt vmcnt(0)
	s_cbranch_scc0 .LBB0_574
	global_load_dwordx4 v[98:101], v[134:135], off
	global_load_dwordx4 v[102:105], v[132:133], off
	global_load_dwordx4 v[106:109], v[130:131], off
	global_load_dwordx4 v[110:113], v[128:129], off

.LBB0_576:
	s_add_i32 s16, s14, 0xffff8000
	s_and_b32 s16, s16, 0x8000
	v_add_u32_e32 v1, s16, v161
	s_waitcnt lgkmcnt(0)
	s_barrier
	v_add_u32_e32 v163, v1, v115
	ds_read_b128 v[2:5], v163
	ds_read_b128 v[6:9], v163 offset:4096
	v_add_u32_e32 v181, v1, v119
	v_add_u32_e32 v222, v1, v158
	s_waitcnt lgkmcnt(1)
	v_mfma_f32_32x32x16_bf16 v[18:33], v[66:69], v[2:5], 0
	v_add_u32_e32 v1, v1, v159
	ds_read_b128 v[34:37], v181
	ds_read_b128 v[38:41], v181 offset:4096
	ds_read_b128 v[42:45], v222
	ds_read_b128 v[46:49], v222 offset:4096
	ds_read_b128 v[50:53], v1
	ds_read_b128 v[54:57], v1 offset:4096
	s_add_i32 s16, s15, 1
	s_cmp_ge_u32 s16, s2
	s_waitcnt lgkmcnt(5)
	v_mfma_f32_32x32x16_bf16 v[18:33], v[70:73], v[34:37], v[18:33]
	ds_read_b128 v[34:37], v163 offset:8192
	ds_read_b128 v[154:157], v163 offset:12288
	ds_read_b128 v[164:167], v181 offset:8192
	ds_read_b128 v[168:171], v181 offset:12288
	ds_read_b128 v[172:175], v222 offset:8192
	ds_read_b128 v[182:185], v222 offset:12288
	ds_read_b128 v[186:189], v1 offset:8192
	ds_read_b128 v[190:193], v1 offset:12288
	v_mfma_f32_32x32x16_bf16 v[2:17], v[66:69], v[6:9], 0
	s_waitcnt lgkmcnt(11)
	v_mfma_f32_32x32x16_bf16 v[18:33], v[74:77], v[42:45], v[18:33]
	ds_read_b128 v[42:45], v163 offset:16384
	ds_read_b128 v[194:197], v163 offset:20480
	ds_read_b128 v[198:201], v181 offset:16384
	ds_read_b128 v[202:205], v181 offset:20480
	ds_read_b128 v[206:209], v222 offset:16384
	ds_read_b128 v[210:213], v222 offset:20480
	ds_read_b128 v[214:217], v1 offset:16384
	ds_read_b128 v[218:221], v1 offset:20480
	v_mfma_f32_32x32x16_bf16 v[2:17], v[70:73], v[38:41], v[2:17]
	s_waitcnt lgkmcnt(14)
	v_mfma_f32_32x32x16_bf16 v[18:33], v[78:81], v[50:53], v[18:33]
	v_mfma_f32_32x32x16_bf16 v[2:17], v[74:77], v[46:49], v[2:17]
	s_nop 10
	v_max_i32_e32 v18, 0, v18
	v_max_i32_e32 v26, 0, v26
	v_max_i32_e32 v19, 0, v19
	v_fma_f32 v223, v86, v18, 0
	v_max_i32_e32 v27, 0, v27
	v_fma_f32 v224, v94, v26, 0
	v_fmac_f32_e32 v223, v87, v19
	v_max_i32_e32 v18, 0, v20
	v_fmac_f32_e32 v224, v95, v27
	v_fmac_f32_e32 v223, v88, v18
	v_max_i32_e32 v18, 0, v28
	v_fmac_f32_e32 v224, v96, v18
	v_max_i32_e32 v18, 0, v21
	v_fmac_f32_e32 v223, v89, v18
	v_max_i32_e32 v18, 0, v29
	v_fmac_f32_e32 v224, v97, v18
	v_max_i32_e32 v18, 0, v22
	v_mfma_f32_32x32x16_bf16 v[2:17], v[78:81], v[54:57], v[2:17]
	v_fmac_f32_e32 v223, v82, v18
	v_max_i32_e32 v18, 0, v30
	v_fmac_f32_e32 v224, v90, v18
	v_max_i32_e32 v18, 0, v23
	v_fmac_f32_e32 v223, v83, v18
	v_max_i32_e32 v18, 0, v31
	v_fmac_f32_e32 v224, v91, v18
	v_mfma_f32_32x32x16_bf16 v[50:65], v[66:69], v[34:37], 0
	v_max_i32_e32 v18, 0, v24
	v_fmac_f32_e32 v223, v84, v18
	v_max_i32_e32 v18, 0, v32
	v_fmac_f32_e32 v224, v92, v18
	v_max_i32_e32 v18, 0, v25
	v_fmac_f32_e32 v223, v85, v18
	v_max_i32_e32 v18, 0, v33
	v_fmac_f32_e32 v224, v93, v18
	v_mfma_f32_32x32x16_bf16 v[18:33], v[66:69], v[154:157], 0
	v_max_i32_e32 v2, 0, v2
	v_fma_f32 v2, v86, v2, 0
	v_max_i32_e32 v10, 0, v10
	v_max_i32_e32 v3, 0, v3
	v_fma_f32 v10, v94, v10, 0
	v_fmac_f32_e32 v2, v87, v3
	v_max_i32_e32 v3, 0, v11
	s_waitcnt lgkmcnt(13)
	v_mfma_f32_32x32x16_bf16 v[50:65], v[70:73], v[164:167], v[50:65]
	v_fmac_f32_e32 v10, v95, v3
	v_max_i32_e32 v3, 0, v4
	v_fmac_f32_e32 v2, v88, v3
	v_max_i32_e32 v3, 0, v12
	v_fmac_f32_e32 v10, v96, v3
	v_max_i32_e32 v3, 0, v5
	v_fmac_f32_e32 v2, v89, v3
	s_waitcnt lgkmcnt(12)
	v_mfma_f32_32x32x16_bf16 v[18:33], v[70:73], v[168:171], v[18:33]
	v_max_i32_e32 v3, 0, v13
	v_fmac_f32_e32 v10, v97, v3
	v_max_i32_e32 v3, 0, v6
	v_fmac_f32_e32 v2, v82, v3
	v_max_i32_e32 v3, 0, v14
	v_fmac_f32_e32 v10, v90, v3
	v_max_i32_e32 v3, 0, v7
	s_waitcnt lgkmcnt(11)
	v_mfma_f32_32x32x16_bf16 v[50:65], v[74:77], v[172:175], v[50:65]
	v_fmac_f32_e32 v2, v83, v3
	v_max_i32_e32 v3, 0, v15
	v_fmac_f32_e32 v10, v91, v3
	v_max_i32_e32 v3, 0, v8
	v_fmac_f32_e32 v2, v84, v3
	v_max_i32_e32 v3, 0, v16
	v_fmac_f32_e32 v10, v92, v3
	v_max_i32_e32 v3, 0, v9
	s_waitcnt lgkmcnt(10)
	v_mfma_f32_32x32x16_bf16 v[18:33], v[74:77], v[182:185], v[18:33]
	v_fmac_f32_e32 v2, v85, v3
	v_max_i32_e32 v3, 0, v17
	v_fmac_f32_e32 v10, v93, v3
	v_cvt_pkrtz_f16_f32 v4, v223, v2
	v_lshl_add_u64 v[2:3], s[80:81], 0, v[150:151]
	v_add_co_u32_e32 v154, vcc, s39, v2
	s_waitcnt lgkmcnt(9)
	v_mfma_f32_32x32x16_bf16 v[50:65], v[78:81], v[186:189], v[50:65]
	v_addc_co_u32_e32 v155, vcc, 0, v3, vcc
	v_add_co_u32_e32 v156, vcc, s40, v2
	global_store_dword v[154:155], v4, off
	v_cvt_pkrtz_f16_f32 v4, v224, v10
	v_addc_co_u32_e32 v157, vcc, 0, v3, vcc
	global_store_dword v[156:157], v4, off
	ds_read_b128 v[164:167], v163 offset:24576
	ds_read_b128 v[168:171], v163 offset:28672
	s_waitcnt lgkmcnt(10)
	v_mfma_f32_32x32x16_bf16 v[18:33], v[78:81], v[190:193], v[18:33]
	ds_read_b128 v[172:175], v181 offset:24576
	ds_read_b128 v[182:185], v181 offset:28672
	ds_read_b128 v[186:189], v222 offset:24576
	ds_read_b128 v[190:193], v222 offset:28672
	ds_read_b128 v[222:225], v1 offset:24576
	ds_read_b128 v[226:229], v1 offset:28672
	v_max_i32_e32 v1, 0, v50
	v_max_i32_e32 v2, 0, v58
	v_fma_f32 v1, v86, v1, 0
	v_fma_f32 v163, v94, v2, 0
	v_max_i32_e32 v2, 0, v51
	v_fmac_f32_e32 v1, v87, v2
	v_max_i32_e32 v2, 0, v59
	s_waitcnt lgkmcnt(14)
	v_mfma_f32_32x32x16_bf16 v[34:49], v[66:69], v[42:45], 0
	v_fmac_f32_e32 v163, v95, v2
	v_max_i32_e32 v50, 0, v52
	v_fmac_f32_e32 v1, v88, v50
	v_max_i32_e32 v50, 0, v60
	v_fmac_f32_e32 v163, v96, v50
	v_max_i32_e32 v50, 0, v53
	v_fmac_f32_e32 v1, v89, v50
	v_mfma_f32_32x32x16_bf16 v[2:17], v[66:69], v[194:197], 0
	v_max_i32_e32 v50, 0, v61
	v_fmac_f32_e32 v163, v97, v50
	v_max_i32_e32 v50, 0, v54
	v_fmac_f32_e32 v1, v82, v50
	v_max_i32_e32 v50, 0, v62
	v_fmac_f32_e32 v163, v90, v50
	v_max_i32_e32 v50, 0, v55
	s_waitcnt lgkmcnt(13)
	v_mfma_f32_32x32x16_bf16 v[34:49], v[70:73], v[198:201], v[34:49]
	v_fmac_f32_e32 v1, v83, v50
	v_max_i32_e32 v50, 0, v63
	v_fmac_f32_e32 v163, v91, v50
	v_max_i32_e32 v50, 0, v56
	v_fmac_f32_e32 v1, v84, v50
	v_max_i32_e32 v50, 0, v64
	v_max_i32_e32 v18, 0, v18
	s_waitcnt lgkmcnt(12)
	v_mfma_f32_32x32x16_bf16 v[2:17], v[70:73], v[202:205], v[2:17]
	v_fmac_f32_e32 v163, v92, v50
	v_max_i32_e32 v50, 0, v57
	v_fma_f32 v181, v86, v18, 0
	v_max_i32_e32 v18, 0, v26
	v_fmac_f32_e32 v1, v85, v50
	v_max_i32_e32 v50, 0, v65
	v_fma_f32 v194, v94, v18, 0
	s_waitcnt lgkmcnt(11)
	v_mfma_f32_32x32x16_bf16 v[34:49], v[74:77], v[206:209], v[34:49]
	v_max_i32_e32 v18, 0, v19
	v_fmac_f32_e32 v163, v93, v50
	v_fmac_f32_e32 v181, v87, v18
	v_max_i32_e32 v18, 0, v27
	v_fmac_f32_e32 v194, v95, v18
	v_max_i32_e32 v18, 0, v20
	v_fmac_f32_e32 v181, v88, v18
	s_waitcnt lgkmcnt(10)
	v_mfma_f32_32x32x16_bf16 v[2:17], v[74:77], v[210:213], v[2:17]
	v_max_i32_e32 v18, 0, v28
	v_fmac_f32_e32 v194, v96, v18
	v_max_i32_e32 v18, 0, v21
	v_fmac_f32_e32 v181, v89, v18
	v_max_i32_e32 v18, 0, v29
	v_fmac_f32_e32 v194, v97, v18
	v_max_i32_e32 v18, 0, v22
	s_waitcnt lgkmcnt(7)
	v_mfma_f32_32x32x16_bf16 v[50:65], v[66:69], v[164:167], 0
	v_fmac_f32_e32 v181, v82, v18
	v_max_i32_e32 v18, 0, v30
	v_fmac_f32_e32 v194, v90, v18
	v_max_i32_e32 v18, 0, v23
	v_fmac_f32_e32 v181, v83, v18
	v_max_i32_e32 v18, 0, v31
	v_fmac_f32_e32 v194, v91, v18
	v_mfma_f32_32x32x16_bf16 v[34:49], v[78:81], v[214:217], v[34:49]
	v_max_i32_e32 v18, 0, v24
	v_fmac_f32_e32 v181, v84, v18
	v_max_i32_e32 v18, 0, v32
	v_fmac_f32_e32 v194, v92, v18
	v_max_i32_e32 v18, 0, v25
	v_fmac_f32_e32 v181, v85, v18
	v_max_i32_e32 v18, 0, v33
	v_mfma_f32_32x32x16_bf16 v[2:17], v[78:81], v[218:221], v[2:17]
	v_fmac_f32_e32 v194, v93, v18
	v_cvt_pkrtz_f16_f32 v1, v1, v181
	global_store_dword v[154:155], v1, off offset:128
	v_cvt_pkrtz_f16_f32 v1, v163, v194
	global_store_dword v[156:157], v1, off offset:128
	v_max_i32_e32 v1, 0, v34
	v_fma_f32 v1, v86, v1, 0
	s_waitcnt lgkmcnt(5)
	v_mfma_f32_32x32x16_bf16 v[50:65], v[70:73], v[172:175], v[50:65]
	s_nop 2
	v_max_i32_e32 v2, 0, v2
	v_max_i32_e32 v34, 0, v42
	v_max_i32_e32 v35, 0, v35
	v_fma_f32 v2, v86, v2, 0
	v_max_i32_e32 v10, 0, v10
	v_max_i32_e32 v3, 0, v3
	v_fma_f32 v34, v94, v34, 0
	v_mfma_f32_32x32x16_bf16 v[18:33], v[66:69], v[168:171], 0
	v_fmac_f32_e32 v1, v87, v35
	v_max_i32_e32 v35, 0, v43
	v_fma_f32 v10, v94, v10, 0
	v_fmac_f32_e32 v2, v87, v3
	v_max_i32_e32 v3, 0, v11
	v_fmac_f32_e32 v34, v95, v35
	v_max_i32_e32 v35, 0, v36
	s_waitcnt lgkmcnt(3)
	v_mfma_f32_32x32x16_bf16 v[50:65], v[74:77], v[186:189], v[50:65]
	v_fmac_f32_e32 v10, v95, v3
	v_max_i32_e32 v3, 0, v4
	v_fmac_f32_e32 v1, v88, v35
	v_max_i32_e32 v35, 0, v44
	v_fmac_f32_e32 v2, v88, v3
	v_max_i32_e32 v3, 0, v12
	v_fmac_f32_e32 v34, v96, v35
	v_max_i32_e32 v35, 0, v37
	v_fmac_f32_e32 v10, v96, v3
	v_max_i32_e32 v3, 0, v5
	v_fmac_f32_e32 v1, v89, v35
	v_max_i32_e32 v35, 0, v45
	v_fmac_f32_e32 v2, v89, v3
	v_max_i32_e32 v3, 0, v13
	v_fmac_f32_e32 v34, v97, v35
	v_max_i32_e32 v35, 0, v38
	v_fmac_f32_e32 v10, v97, v3
	v_max_i32_e32 v3, 0, v6
	v_mfma_f32_32x32x16_bf16 v[18:33], v[70:73], v[182:185], v[18:33]
	v_fmac_f32_e32 v1, v82, v35
	v_max_i32_e32 v35, 0, v46
	v_fmac_f32_e32 v2, v82, v3
	v_max_i32_e32 v3, 0, v14
	v_fmac_f32_e32 v34, v90, v35
	v_max_i32_e32 v35, 0, v39
	v_fmac_f32_e32 v10, v90, v3
	s_waitcnt lgkmcnt(1)
	v_mfma_f32_32x32x16_bf16 v[50:65], v[78:81], v[222:225], v[50:65]
	v_max_i32_e32 v3, 0, v7
	v_fmac_f32_e32 v1, v83, v35
	v_max_i32_e32 v35, 0, v47
	v_fmac_f32_e32 v2, v83, v3
	v_max_i32_e32 v3, 0, v15
	v_fmac_f32_e32 v34, v91, v35
	v_max_i32_e32 v35, 0, v40
	v_fmac_f32_e32 v10, v91, v3
	v_max_i32_e32 v3, 0, v8
	v_fmac_f32_e32 v1, v84, v35
	v_max_i32_e32 v35, 0, v48
	v_fmac_f32_e32 v2, v84, v3
	v_max_i32_e32 v3, 0, v16
	v_fmac_f32_e32 v34, v92, v35
	v_max_i32_e32 v35, 0, v41
	v_fmac_f32_e32 v10, v92, v3
	v_max_i32_e32 v3, 0, v9
	v_fmac_f32_e32 v1, v85, v35
	v_max_i32_e32 v35, 0, v49
	v_fmac_f32_e32 v2, v85, v3
	v_max_i32_e32 v3, 0, v17
	v_fmac_f32_e32 v34, v93, v35
	v_fmac_f32_e32 v10, v93, v3
	v_cvt_pkrtz_f16_f32 v1, v1, v2
	v_mfma_f32_32x32x16_bf16 v[18:33], v[74:77], v[190:193], v[18:33]
	global_store_dword v[154:155], v1, off offset:256
	v_cvt_pkrtz_f16_f32 v1, v34, v10
	global_store_dword v[156:157], v1, off offset:256
	v_max_i32_e32 v1, 0, v50
	v_fma_f32 v1, v86, v1, 0
	v_max_i32_e32 v2, 0, v58
	v_max_i32_e32 v3, 0, v51
	v_fma_f32 v2, v94, v2, 0
	v_fmac_f32_e32 v1, v87, v3
	v_max_i32_e32 v3, 0, v59
	v_fmac_f32_e32 v2, v95, v3
	v_max_i32_e32 v3, 0, v52
	v_fmac_f32_e32 v1, v88, v3
	v_max_i32_e32 v3, 0, v60
	v_fmac_f32_e32 v2, v96, v3
	v_max_i32_e32 v3, 0, v53
	v_fmac_f32_e32 v1, v89, v3
	v_max_i32_e32 v3, 0, v61
	s_waitcnt lgkmcnt(0)
	v_mfma_f32_32x32x16_bf16 v[18:33], v[78:81], v[226:229], v[18:33]
	v_fmac_f32_e32 v2, v97, v3
	v_max_i32_e32 v3, 0, v54
	v_fmac_f32_e32 v1, v82, v3
	v_max_i32_e32 v3, 0, v62
	v_fmac_f32_e32 v2, v90, v3
	v_max_i32_e32 v3, 0, v55
	v_fmac_f32_e32 v1, v83, v3
	v_max_i32_e32 v3, 0, v63
	v_fmac_f32_e32 v2, v91, v3
	v_max_i32_e32 v3, 0, v56
	v_fmac_f32_e32 v1, v84, v3
	v_max_i32_e32 v3, 0, v64
	v_fmac_f32_e32 v2, v92, v3
	v_max_i32_e32 v3, 0, v57
	v_fmac_f32_e32 v1, v85, v3
	v_max_i32_e32 v3, 0, v65
	v_fmac_f32_e32 v2, v93, v3
	v_max_i32_e32 v3, 0, v18
	v_fma_f32 v3, v86, v3, 0
	v_max_i32_e32 v4, 0, v26
	v_max_i32_e32 v5, 0, v19
	v_fma_f32 v4, v94, v4, 0
	v_fmac_f32_e32 v3, v87, v5
	v_max_i32_e32 v5, 0, v27
	v_fmac_f32_e32 v4, v95, v5
	v_max_i32_e32 v5, 0, v20
	v_fmac_f32_e32 v3, v88, v5
	v_max_i32_e32 v5, 0, v28
	v_fmac_f32_e32 v4, v96, v5
	v_max_i32_e32 v5, 0, v21
	v_fmac_f32_e32 v3, v89, v5
	v_max_i32_e32 v5, 0, v29
	v_fmac_f32_e32 v4, v97, v5
	v_max_i32_e32 v5, 0, v22
	v_fmac_f32_e32 v3, v82, v5
	v_max_i32_e32 v5, 0, v30
	v_fmac_f32_e32 v4, v90, v5
	v_max_i32_e32 v5, 0, v23
	v_fmac_f32_e32 v3, v83, v5
	v_max_i32_e32 v5, 0, v31
	v_fmac_f32_e32 v4, v91, v5
	v_max_i32_e32 v5, 0, v24
	v_fmac_f32_e32 v3, v84, v5
	v_max_i32_e32 v5, 0, v32
	v_fmac_f32_e32 v4, v92, v5
	v_max_i32_e32 v5, 0, v25
	v_fmac_f32_e32 v3, v85, v5
	v_max_i32_e32 v5, 0, v33
	v_fmac_f32_e32 v4, v93, v5
	v_cvt_pkrtz_f16_f32 v1, v1, v3
	global_store_dword v[154:155], v1, off offset:384
	v_cvt_pkrtz_f16_f32 v1, v2, v4
	global_store_dword v[156:157], v1, off offset:384
	s_cbranch_scc1 .LBB0_575
	s_and_b32 s17, s14, 0x8000
	s_add_i32 s15, s15, 2
	v_add_u32_e32 v1, s17, v160
	s_cmp_ge_u32 s15, s2
	s_waitcnt vmcnt(8)
	ds_write_b128 v1, v[98:101]
	ds_write_b128 v1, v[102:105] offset:8192
	ds_write_b128 v1, v[106:109] offset:16384
	ds_write_b128 v1, v[110:113] offset:24576
	s_cbranch_scc1 .LBB0_575
	v_lshl_add_u64 v[2:3], s[80:81], 0, v[152:153]
	v_add_co_u32_e32 v4, vcc, 0xa410000, v2
	s_nop 1
	v_addc_co_u32_e32 v5, vcc, 0, v3, vcc
	v_add_co_u32_e32 v6, vcc, 0xa412000, v2
	s_nop 1
	v_addc_co_u32_e32 v7, vcc, 0, v3, vcc
	global_load_dwordx4 v[98:101], v[4:5], off
	global_load_dwordx4 v[102:105], v[6:7], off
	v_add_co_u32_e32 v4, vcc, 0xa414000, v2
	s_nop 1
	v_addc_co_u32_e32 v5, vcc, 0, v3, vcc
	v_add_co_u32_e32 v2, vcc, 0xa416000, v2
	s_nop 1
	v_addc_co_u32_e32 v3, vcc, 0, v3, vcc
	global_load_dwordx4 v[106:109], v[4:5], off
	global_load_dwordx4 v[110:113], v[2:3], off
	s_branch .LBB0_575

.LBB0_825:
	s_or_b64 exec, exec, s[20:21]
	v_lshl_add_u64 v[10:11], v[32:33], 0, v[26:27]
	v_add_co_u32_e32 v12, vcc, 0xe900000, v10
	v_addc_co_u32_e32 v13, vcc, 0, v11, vcc
	global_load_dwordx4 v[38:41], v[12:13], off offset:3072
	v_add_co_u32_e32 v12, vcc, 0xe901000, v10
	s_nop 0
	v_addc_co_u32_e32 v13, vcc, 0, v11, vcc
	global_load_dwordx4 v[18:21], v[12:13], off offset:2624
	v_add_co_u32_e32 v12, vcc, 0xe902000, v10
	s_nop 0
	v_addc_co_u32_e32 v13, vcc, 0, v11, vcc
	v_add_co_u32_e32 v10, vcc, 0xe903000, v10
	s_nop 0
	v_addc_co_u32_e32 v11, vcc, 0, v11, vcc
	global_load_dwordx4 v[14:17], v[12:13], off offset:2176
	s_nop 0
	global_load_dwordx4 v[10:13], v[10:11], off offset:1728
	s_waitcnt vmcnt(4)
	v_lshlrev_b32_e32 v44, 16, v22
	v_and_b32_e32 v45, 0xffff0000, v22
	v_lshlrev_b32_e32 v22, 16, v23
	v_and_b32_e32 v23, 0xffff0000, v23
	v_lshlrev_b32_e32 v46, 16, v24
	v_and_b32_e32 v47, 0xffff0000, v24
	v_lshlrev_b32_e32 v24, 16, v25
	v_and_b32_e32 v25, 0xffff0000, v25
	s_waitcnt vmcnt(3)
	v_lshlrev_b32_e32 v42, 16, v38
	v_and_b32_e32 v43, 0xffff0000, v38
	v_lshlrev_b32_e32 v38, 16, v39
	v_and_b32_e32 v39, 0xffff0000, v39
	v_lshlrev_b32_e32 v36, 16, v40
	v_and_b32_e32 v37, 0xffff0000, v40
	v_lshlrev_b32_e32 v34, 16, v41
	v_and_b32_e32 v35, 0xffff0000, v41
	v_pk_add_f32 v[40:41], v[44:45], v[42:43] neg_lo:[0,1] neg_hi:[0,1]
	v_pk_add_f32 v[22:23], v[22:23], v[38:39] neg_lo:[0,1] neg_hi:[0,1]
	v_pk_add_f32 v[46:47], v[46:47], v[36:37] neg_lo:[0,1] neg_hi:[0,1]
	v_pk_add_f32 v[48:49], v[24:25], v[34:35] neg_lo:[0,1] neg_hi:[0,1]
	v_pk_fma_f32 v[44:45], v[6:7], v[40:41], v[42:43]
	v_pk_fma_f32 v[40:41], v[8:9], v[22:23], v[38:39]
	v_pk_fma_f32 v[24:25], v[2:3], v[46:47], v[36:37]
	v_pk_fma_f32 v[22:23], v[4:5], v[48:49], v[34:35]
	s_and_saveexec_b64 s[20:21], s[0:1]
	s_xor_b64 s[20:21], exec, s[20:21]
	s_cbranch_execz .LBB0_829
	s_and_saveexec_b64 s[22:23], s[4:5]
	s_cbranch_execz .LBB0_828
	v_mul_f32_e32 v44, 0xbfb8aa3b, v44
	v_mul_f32_e32 v45, 0xbfb8aa3b, v45
	v_mul_f32_e32 v40, 0xbfb8aa3b, v40
	v_mul_f32_e32 v41, 0xbfb8aa3b, v41
	v_mul_f32_e32 v24, 0xbfb8aa3b, v24
	v_mul_f32_e32 v25, 0xbfb8aa3b, v25
	v_mul_f32_e32 v22, 0xbfb8aa3b, v22
	v_mul_f32_e32 v23, 0xbfb8aa3b, v23
	v_exp_f32_e32 v44, v44
	v_exp_f32_e32 v45, v45
	v_exp_f32_e32 v40, v40
	v_exp_f32_e32 v41, v41
	v_exp_f32_e32 v24, v24
	v_exp_f32_e32 v25, v25
	v_exp_f32_e32 v22, v22
	v_exp_f32_e32 v23, v23
	v_add_f32_e32 v44, 1.0, v44
	v_add_f32_e32 v45, 1.0, v45
	v_add_f32_e32 v40, 1.0, v40
	v_add_f32_e32 v41, 1.0, v41
	v_add_f32_e32 v24, 1.0, v24
	v_add_f32_e32 v25, 1.0, v25
	v_add_f32_e32 v22, 1.0, v22
	v_add_f32_e32 v23, 1.0, v23
	v_rcp_f32_e32 v44, v44
	v_rcp_f32_e32 v45, v45
	v_rcp_f32_e32 v40, v40
	v_rcp_f32_e32 v41, v41
	v_rcp_f32_e32 v24, v24
	v_rcp_f32_e32 v25, v25
	v_rcp_f32_e32 v22, v22
	v_rcp_f32_e32 v23, v23
